# rope loops of layer-1 in-proj epilogue: each iteration first touches the cos/sin table rows of the next three iterations (cache prefetch into a scratch VGPR)
# speedup vs baseline: 1.0037x; 1.0037x over previous
; DI int TID() { int t = threadIdx.x; asm volatile("" : "+v"(t)); return t; }
; DI void rope_inplace(float* Cs, int cb, int HALF, const float* cs, int tstride, int idx0, int pos0) {
;   const int cpr = HALF >> 3;
;   for (int u = TID(); u < 128 * cpr; u += NT) {
;     int row = u / cpr, c8 = (u % cpr) * 8; float a[8], b[8];
;     ldrow8(Cs, row, cb + c8, a); ldrow8(Cs, row, cb + HALF + c8, b);
;     const float* t = cs + (long)(pos0 + row) * tstride + (idx0 + c8) * 2;
;     for (int j = 0; j < 8; ++j) { float co = t[2 * j], si = t[2 * j + 1]; float x1 = a[j], x2 = b[j]; a[j] = x1 * co - x2 * si; b[j] = x1 * si + x2 * co; }
;     f32x4 o;
;     o = (f32x4){a[0], a[1], a[2], a[3]}; *(f32x4*)(Cs + row * CLD + cb + c8) = o;
;     o = (f32x4){a[4], a[5], a[6], a[7]}; *(f32x4*)(Cs + row * CLD + cb + c8 + 4) = o;
;     o = (f32x4){b[0], b[1], b[2], b[3]}; *(f32x4*)(Cs + row * CLD + cb + HALF + c8) = o;
;     o = (f32x4){b[4], b[5], b[6], b[7]}; *(f32x4*)(Cs + row * CLD + cb + HALF + c8 + 4) = o;
;   }
.LBB0_1313:
	v_ashrrev_i32_e32 v179, 31, v177
	v_lshrrev_b32_e32 v179, 29, v179
	v_add_u32_e32 v179, v177, v179
	v_ashrrev_i32_e32 v179, 3, v179
	v_add_u32_e32 v206, s7, v179
	v_mad_u64_u32 v[200:201], s[34:35], v179, s60, v[176:177]
	v_ashrrev_i32_e32 v207, 31, v206
	v_lshlrev_b32_e32 v179, 7, v179
	v_lshlrev_b64 v[206:207], 10, v[206:207]
	v_sub_u32_e32 v224, v178, v179
	v_lshl_add_u64 v[206:207], s[36:37], 0, v[206:207]
	v_ashrrev_i32_e32 v225, 31, v224
	v_lshl_add_u64 v[206:207], v[224:225], 2, v[206:207]
	s_mov_b32 s98, 0x8000
	s_mov_b32 s99, 0
	v_lshl_add_u64 v[252:253], s[98:99], 0, v[206:207]
	global_load_dword v251, v[252:253], off
	v_lshl_add_u64 v[252:253], s[98:99], 0, v[252:253]
	global_load_dword v251, v[252:253], off
	v_lshl_add_u64 v[252:253], s[98:99], 0, v[252:253]
	global_load_dword v251, v[252:253], off
	ds_read_b128 v[180:183], v200
	ds_read_b128 v[188:191], v200 offset:16
	ds_read_b128 v[192:195], v200 offset:256
	ds_read_b128 v[196:199], v200 offset:272
	global_load_dwordx4 v[224:227], v[206:207], off offset:48
	global_load_dwordx4 v[228:231], v[206:207], off offset:32
	global_load_dwordx4 v[232:235], v[206:207], off offset:16
	global_load_dwordx4 v[236:239], v[206:207], off
	v_add_u32_e32 v179, 0x100, v177
	v_cmp_lt_i32_e32 vcc, s87, v177
	v_add_u32_e32 v178, 0x1000, v178
	v_add_u32_e32 v176, 0x2000, v176
	s_or_b64 s[2:3], vcc, s[2:3]
	v_mov_b32_e32 v177, v179
	s_waitcnt vmcnt(0)
	v_mov_b32_e32 v206, v237
	v_mov_b32_e32 v207, v239
	s_waitcnt lgkmcnt(0)
	v_pk_mul_f32 v[240:241], v[180:181], v[206:207]
	v_mov_b32_e32 v237, v238
	v_pk_fma_f32 v[238:239], v[192:193], v[236:237], v[240:241]
	v_pk_mul_f32 v[192:193], v[192:193], v[206:207]
	s_nop 0
	v_pk_fma_f32 v[180:181], v[180:181], v[236:237], v[192:193] neg_lo:[0,0,1] neg_hi:[0,0,1]
	v_mov_b32_e32 v192, v233
	v_mov_b32_e32 v193, v235
	v_pk_mul_f32 v[206:207], v[182:183], v[192:193]
	v_mov_b32_e32 v233, v234
	v_pk_fma_f32 v[240:241], v[194:195], v[232:233], v[206:207]
	v_pk_mul_f32 v[192:193], v[194:195], v[192:193]
	v_mov_b32_e32 v194, v229
	v_mov_b32_e32 v195, v231
	v_pk_fma_f32 v[182:183], v[182:183], v[232:233], v[192:193] neg_lo:[0,0,1] neg_hi:[0,0,1]
	v_pk_mul_f32 v[192:193], v[188:189], v[194:195]
	v_mov_b32_e32 v229, v230
	v_pk_fma_f32 v[192:193], v[196:197], v[228:229], v[192:193]
	v_pk_mul_f32 v[194:195], v[196:197], v[194:195]
	v_mov_b32_e32 v196, v225
	v_mov_b32_e32 v197, v227
	v_pk_fma_f32 v[188:189], v[188:189], v[228:229], v[194:195] neg_lo:[0,0,1] neg_hi:[0,0,1]
	v_pk_mul_f32 v[194:195], v[190:191], v[196:197]
	v_mov_b32_e32 v225, v226
	v_pk_mul_f32 v[196:197], v[198:199], v[196:197]
	v_pk_fma_f32 v[194:195], v[198:199], v[224:225], v[194:195]
	v_pk_fma_f32 v[190:191], v[190:191], v[224:225], v[196:197] neg_lo:[0,0,1] neg_hi:[0,0,1]
	ds_write_b128 v200, v[180:183]
	ds_write_b128 v200, v[188:191] offset:16
	ds_write_b128 v200, v[238:241] offset:256
	ds_write_b128 v200, v[192:195] offset:272
	s_andn2_b64 exec, exec, s[2:3]
	s_cbranch_execnz .LBB0_1313

; DI int TID() { int t = threadIdx.x; asm volatile("" : "+v"(t)); return t; }
; DI void rope_inplace(float* Cs, int cb, int HALF, const float* cs, int tstride, int idx0, int pos0) {
;   const int cpr = HALF >> 3;
;   for (int u = TID(); u < 128 * cpr; u += NT) {
;     int row = u / cpr, c8 = (u % cpr) * 8; float a[8], b[8];
;     ldrow8(Cs, row, cb + c8, a); ldrow8(Cs, row, cb + HALF + c8, b);
;     const float* t = cs + (long)(pos0 + row) * tstride + (idx0 + c8) * 2;
;     for (int j = 0; j < 8; ++j) { float co = t[2 * j], si = t[2 * j + 1]; float x1 = a[j], x2 = b[j]; a[j] = x1 * co - x2 * si; b[j] = x1 * si + x2 * co; }
;     f32x4 o;
;     o = (f32x4){a[0], a[1], a[2], a[3]}; *(f32x4*)(Cs + row * CLD + cb + c8) = o;
;     o = (f32x4){a[4], a[5], a[6], a[7]}; *(f32x4*)(Cs + row * CLD + cb + c8 + 4) = o;
;     o = (f32x4){b[0], b[1], b[2], b[3]}; *(f32x4*)(Cs + row * CLD + cb + HALF + c8) = o;
;     o = (f32x4){b[4], b[5], b[6], b[7]}; *(f32x4*)(Cs + row * CLD + cb + HALF + c8 + 4) = o;
;   }
.LBB0_1386:
	v_ashrrev_i32_e32 v3, 31, v1
	v_lshrrev_b32_e32 v3, 29, v3
	v_add_u32_e32 v3, v1, v3
	v_ashrrev_i32_e32 v3, 3, v3
	v_add_u32_e32 v20, s7, v3
	v_mad_u64_u32 v[38:39], s[24:25], v3, s60, v[0:1]
	v_ashrrev_i32_e32 v21, 31, v20
	v_lshlrev_b32_e32 v3, 7, v3
	v_lshlrev_b64 v[20:21], 10, v[20:21]
	v_sub_u32_e32 v22, v2, v3
	v_lshl_add_u64 v[20:21], s[26:27], 0, v[20:21]
	v_ashrrev_i32_e32 v23, 31, v22
	v_lshl_add_u64 v[32:33], v[22:23], 2, v[20:21]
	s_mov_b32 s98, 0x8000
	s_mov_b32 s99, 0
	v_lshl_add_u64 v[252:253], s[98:99], 0, v[32:33]
	global_load_dword v251, v[252:253], off
	v_lshl_add_u64 v[252:253], s[98:99], 0, v[252:253]
	global_load_dword v251, v[252:253], off
	v_lshl_add_u64 v[252:253], s[98:99], 0, v[252:253]
	global_load_dword v251, v[252:253], off
	ds_read_b128 v[4:7], v38
	s_waitcnt lgkmcnt(0)
	ds_read_b128 v[8:11], v38 offset:16
	ds_read_b128 v[12:15], v38 offset:256
	ds_read_b128 v[16:19], v38 offset:272
	global_load_dwordx4 v[20:23], v[32:33], off offset:48
	global_load_dwordx4 v[24:27], v[32:33], off offset:32
	global_load_dwordx4 v[28:31], v[32:33], off offset:16
	s_nop 0
	global_load_dwordx4 v[32:35], v[32:33], off
	v_add_u32_e32 v3, 0x100, v1
	v_cmp_lt_i32_e32 vcc, s87, v1
	v_add_u32_e32 v2, 0x1000, v2
	v_add_u32_e32 v0, 0x2000, v0
	s_or_b64 s[14:15], vcc, s[14:15]
	v_mov_b32_e32 v1, v3
	s_waitcnt vmcnt(0)
	v_mov_b32_e32 v36, v33
	v_mov_b32_e32 v37, v35
	v_pk_mul_f32 v[40:41], v[4:5], v[36:37]
	v_mov_b32_e32 v33, v34
	s_waitcnt lgkmcnt(1)
	v_pk_fma_f32 v[34:35], v[12:13], v[32:33], v[40:41]
	v_pk_mul_f32 v[12:13], v[12:13], v[36:37]
	s_nop 0
	v_pk_fma_f32 v[4:5], v[4:5], v[32:33], v[12:13] neg_lo:[0,0,1] neg_hi:[0,0,1]
	v_mov_b32_e32 v12, v29
	v_mov_b32_e32 v13, v31
	v_pk_mul_f32 v[32:33], v[6:7], v[12:13]
	v_mov_b32_e32 v29, v30
	v_pk_fma_f32 v[36:37], v[14:15], v[28:29], v[32:33]
	v_pk_mul_f32 v[12:13], v[14:15], v[12:13]
	v_mov_b32_e32 v14, v25
	v_mov_b32_e32 v15, v27
	v_pk_fma_f32 v[6:7], v[6:7], v[28:29], v[12:13] neg_lo:[0,0,1] neg_hi:[0,0,1]
	v_pk_mul_f32 v[12:13], v[8:9], v[14:15]
	v_mov_b32_e32 v25, v26
	s_waitcnt lgkmcnt(0)
	v_pk_fma_f32 v[12:13], v[16:17], v[24:25], v[12:13]
	v_pk_mul_f32 v[14:15], v[16:17], v[14:15]
	v_mov_b32_e32 v16, v21
	v_mov_b32_e32 v17, v23
	v_pk_fma_f32 v[8:9], v[8:9], v[24:25], v[14:15] neg_lo:[0,0,1] neg_hi:[0,0,1]
	v_pk_mul_f32 v[14:15], v[10:11], v[16:17]
	v_mov_b32_e32 v21, v22
	v_pk_mul_f32 v[16:17], v[18:19], v[16:17]
	v_pk_fma_f32 v[14:15], v[18:19], v[20:21], v[14:15]
	v_pk_fma_f32 v[10:11], v[10:11], v[20:21], v[16:17] neg_lo:[0,0,1] neg_hi:[0,0,1]
	ds_write_b128 v38, v[4:7]
	ds_write_b128 v38, v[8:11] offset:16
	ds_write_b128 v38, v[34:37] offset:256
	ds_write_b128 v38, v[12:15] offset:272
	s_andn2_b64 exec, exec, s[14:15]
	s_cbranch_execnz .LBB0_1386
